# P2 residual epilogue: f32 base loads for three row blocks kept in flight in a register ring, counted waits
# baseline (speedup 1.0000x reference)
; __device__ __forceinline__ unsigned cvtpk(float lo, float hi) { f32x2_t v = {lo, hi}; bf16x2_t b = __builtin_convertvector(v, bf16x2_t); return __builtin_bit_cast(unsigned, b); }
; __device__ __forceinline__ float bflo(unsigned w) { return __uint_as_float(w << 16); }
; __device__ __forceinline__ float bfhi(unsigned w) { return __uint_as_float(w & 0xffff0000u); }
;     __device__ __forceinline__ void operator()(const f32x4 (&acc)[2][2][4][2], const Unit& u, int wr, int wc, int fr, int fq) const {
;         const int row0 = u.pm * 256 + wr * 64 + fr, col0 = (u.pn & 7) * 256 + wc * 32 + 8 * fq;
; #pragma unroll
;         for (int ai = 0; ai < 2; ++ai)
; #pragma unroll
;             for (int m = 0; m < 4; ++m) {
;                 const int row = row0 + ai * 128 + m * 16; float s = 0.f;
; #pragma unroll
;                 for (int bj = 0; bj < 2; ++bj) {
;                     const size_t off = (size_t)row * D + col0 + bj * 128;
;                     f32x4 b0, b1;
;                     if (BASE_F32) { b0 = __builtin_nontemporal_load((const f32x4*)(base + off)); b1 = __builtin_nontemporal_load((const f32x4*)(base + off + 4)); }
;                     else { const u32x4 w = *(const u32x4*)(xb + off); b0 = (f32x4){bflo(w.x), bfhi(w.x), bflo(w.y), bfhi(w.y)}; b1 = (f32x4){bflo(w.z), bfhi(w.z), bflo(w.w), bfhi(w.w)}; }
;                     const f32x4 h0 = b0 + acc[ai][bj][m][0] * scale, h1 = b1 + acc[ai][bj][m][1] * scale;
;                     if (OUT_F32) { *(f32x4*)(out + off) = h0; *(f32x4*)(out + off + 4) = h1; }
;                     else { u32x4 w; w.x = cvtpk(h0[0], h0[1]); w.y = cvtpk(h0[2], h0[3]); w.z = cvtpk(h1[0], h1[1]); w.w = cvtpk(h1[2], h1[3]); st16(xb + off, w); }
;                     s += (h0[0] * h0[0] + h0[1] * h0[1]) + (h0[2] * h0[2] + h0[3] * h0[3]) + (h1[0] * h1[0] + h1[1] * h1[1]) + (h1[2] * h1[2] + h1[3] * h1[3]);
;                 }
;                 s += __shfl_xor(s, 16); s += __shfl_xor(s, 32);
;                 if (fq == 0) __hip_atomic_fetch_add(ssq_out + row, s, __ATOMIC_RELAXED, __HIP_MEMORY_SCOPE_AGENT);
.LBB0_611:
	v_and_b32_e32 v147, 64, v156
	v_xor_b32_e32 v146, 16, v156
	v_add_u32_e32 v147, 64, v147
	v_cmp_lt_i32_e32 vcc, v146, v147
	v_lshl_add_u32 v148, s33, 8, v150
	s_lshl_b32 s26, s52, 8
	v_cndmask_b32_e32 v146, v156, v146, vcc
	v_lshlrev_b32_e32 v158, 2, v146
	v_xor_b32_e32 v146, 32, v156
	v_cmp_lt_i32_e32 vcc, v146, v147
	s_and_b32 s26, s26, 0x700
	v_ashrrev_i32_e32 v149, 31, v148
	v_cndmask_b32_e32 v146, v156, v146, vcc
	v_or_b32_e32 v159, s26, v152
	v_lshlrev_b32_e32 v157, 2, v146
	v_lshlrev_b64 v[146:147], 11, v[148:149]
	v_or_b32_e32 v146, v146, v159
	v_lshl_add_u64 v[168:169], v[146:147], 2, s[68:69]
	global_load_dwordx4 v[172:175], v[168:169], off offset:16 nt
	global_load_dwordx4 v[176:179], v[168:169], off nt
	global_load_dwordx4 v[180:183], v[168:169], off offset:528 nt
	global_load_dwordx4 v[184:187], v[168:169], off offset:512 nt
	s_mov_b64 s[100:101], 0x20000
	v_lshl_add_u64 v[170:171], v[168:169], 0, s[100:101]
	global_load_dwordx4 v[192:195], v[170:171], off offset:16 nt
	global_load_dwordx4 v[196:199], v[170:171], off nt
	global_load_dwordx4 v[200:203], v[170:171], off offset:528 nt
	global_load_dwordx4 v[204:207], v[170:171], off offset:512 nt
	s_mov_b64 s[100:101], 0x40000
	v_lshl_add_u64 v[170:171], v[168:169], 0, s[100:101]
	global_load_dwordx4 v[208:211], v[170:171], off offset:16 nt
	global_load_dwordx4 v[212:215], v[170:171], off nt
	global_load_dwordx4 v[216:219], v[170:171], off offset:528 nt
	global_load_dwordx4 v[220:223], v[170:171], off offset:512 nt
	s_waitcnt vmcnt(10)
	v_pk_fma_f32 v[162:163], v[124:125], 0.5, v[174:175] op_sel_hi:[1,0,1]
	v_pk_fma_f32 v[128:129], v[128:129], 0.5, v[178:179] op_sel_hi:[1,0,1]
	v_pk_fma_f32 v[126:127], v[126:127], 0.5, v[176:177] op_sel_hi:[1,0,1]
	v_pk_fma_f32 v[160:161], v[122:123], 0.5, v[172:173] op_sel_hi:[1,0,1]
	v_lshlrev_b64 v[164:165], 1, v[146:147]
	v_cvt_pk_bf16_f32 v122, v126, v127
	v_cvt_pk_bf16_f32 v123, v128, v129
	v_cvt_pk_bf16_f32 v124, v160, v161
	v_cvt_pk_bf16_f32 v125, v162, v163
	v_lshl_add_u64 v[166:167], s[36:37], 0, v[164:165]
	global_store_dwordx4 v[166:167], v[122:125], off
	v_or_b32_e32 v164, 0x100, v164
	s_nop 0
	v_mul_f32_e32 v122, v127, v127
	v_mul_f32_e32 v123, v129, v129
	v_fmac_f32_e32 v122, v126, v126
	v_fmac_f32_e32 v123, v128, v128
	v_add_f32_e32 v122, v122, v123
	v_mul_f32_e32 v123, v161, v161
	v_fmac_f32_e32 v123, v160, v160
	v_add_f32_e32 v122, v123, v122
	v_mul_f32_e32 v123, v163, v163
	v_fmac_f32_e32 v123, v162, v162
	v_add_f32_e32 v160, v123, v122
	s_waitcnt vmcnt(10)
	v_pk_fma_f32 v[124:125], v[116:117], 0.5, v[182:183] op_sel_hi:[1,0,1]
	s_waitcnt vmcnt(9)
	v_pk_fma_f32 v[120:121], v[120:121], 0.5, v[186:187] op_sel_hi:[1,0,1]
	v_pk_fma_f32 v[118:119], v[118:119], 0.5, v[184:185] op_sel_hi:[1,0,1]
	v_pk_fma_f32 v[122:123], v[114:115], 0.5, v[180:181] op_sel_hi:[1,0,1]
	s_mov_b64 s[100:101], 0x60000
	v_lshl_add_u64 v[170:171], v[168:169], 0, s[100:101]
	global_load_dwordx4 v[172:175], v[170:171], off offset:16 nt
	global_load_dwordx4 v[176:179], v[170:171], off nt
	global_load_dwordx4 v[180:183], v[170:171], off offset:528 nt
	global_load_dwordx4 v[184:187], v[170:171], off offset:512 nt
	v_cvt_pk_bf16_f32 v114, v118, v119
	v_cvt_pk_bf16_f32 v115, v120, v121
	v_cvt_pk_bf16_f32 v116, v122, v123
	v_cvt_pk_bf16_f32 v117, v124, v125
	v_lshl_add_u64 v[126:127], s[36:37], 0, v[164:165]
	global_store_dwordx4 v[126:127], v[114:117], off
	s_nop 1
	v_mul_f32_e32 v114, v119, v119
	v_mul_f32_e32 v115, v121, v121
	v_fmac_f32_e32 v114, v118, v118
	v_fmac_f32_e32 v115, v120, v120
	v_add_f32_e32 v114, v114, v115
	v_mul_f32_e32 v115, v123, v123
	v_fmac_f32_e32 v115, v122, v122
	v_add_f32_e32 v114, v115, v114
	v_mul_f32_e32 v115, v125, v125
	v_fmac_f32_e32 v115, v124, v124
	v_add_f32_e32 v114, v115, v114
	v_add_f32_e32 v114, v160, v114
	ds_bpermute_b32 v115, v158, v114
	s_waitcnt lgkmcnt(0)
	v_add_f32_e32 v116, v114, v115
	ds_bpermute_b32 v117, v157, v116
	v_lshl_add_u64 v[114:115], v[148:149], 2, s[16:17]
	s_and_saveexec_b64 s[26:27], s[0:1]
	s_cbranch_execz .LBB0_613
	s_waitcnt lgkmcnt(0)
	v_add_f32_e32 v116, v116, v117
	global_atomic_add_f32 v[114:115], v116, off
.LBB0_613:
	s_or_b64 exec, exec, s[26:27]
	v_or_b32_e32 v116, 16, v148
	s_waitcnt lgkmcnt(0)
	v_ashrrev_i32_e32 v117, 31, v116
	v_lshlrev_b64 v[124:125], 11, v[116:117]
	v_or_b32_e32 v124, v124, v159
	v_lshl_add_u64 v[126:127], v[124:125], 2, s[68:69]
	s_waitcnt vmcnt(13)
	v_pk_fma_f32 v[118:119], v[108:109], 0.5, v[194:195] op_sel_hi:[1,0,1]
	s_waitcnt vmcnt(12)
	v_pk_fma_f32 v[112:113], v[112:113], 0.5, v[198:199] op_sel_hi:[1,0,1]
	v_pk_fma_f32 v[110:111], v[110:111], 0.5, v[196:197] op_sel_hi:[1,0,1]
	v_pk_fma_f32 v[116:117], v[106:107], 0.5, v[192:193] op_sel_hi:[1,0,1]
	v_lshlrev_b64 v[120:121], 1, v[124:125]
	v_cvt_pk_bf16_f32 v106, v110, v111
	v_cvt_pk_bf16_f32 v107, v112, v113
	v_cvt_pk_bf16_f32 v108, v116, v117
	v_cvt_pk_bf16_f32 v109, v118, v119
	v_lshl_add_u64 v[122:123], s[36:37], 0, v[120:121]
	global_store_dwordx4 v[122:123], v[106:109], off
	v_or_b32_e32 v120, 0x100, v120
	s_nop 0
	v_mul_f32_e32 v106, v111, v111
	v_mul_f32_e32 v107, v113, v113
	v_fmac_f32_e32 v106, v110, v110
	v_fmac_f32_e32 v107, v112, v112
	v_add_f32_e32 v106, v106, v107
	v_mul_f32_e32 v107, v117, v117
	v_fmac_f32_e32 v107, v116, v116
	v_add_f32_e32 v106, v107, v106
	v_mul_f32_e32 v107, v119, v119
	v_fmac_f32_e32 v107, v118, v118
	v_add_f32_e32 v116, v107, v106
	s_waitcnt vmcnt(12)
	v_pk_fma_f32 v[108:109], v[100:101], 0.5, v[202:203] op_sel_hi:[1,0,1]
	s_waitcnt vmcnt(11)
	v_pk_fma_f32 v[104:105], v[104:105], 0.5, v[206:207] op_sel_hi:[1,0,1]
	v_pk_fma_f32 v[102:103], v[102:103], 0.5, v[204:205] op_sel_hi:[1,0,1]
	v_pk_fma_f32 v[106:107], v[98:99], 0.5, v[200:201] op_sel_hi:[1,0,1]
	s_mov_b64 s[100:101], 0x100000
	v_lshl_add_u64 v[170:171], v[168:169], 0, s[100:101]
	global_load_dwordx4 v[192:195], v[170:171], off offset:16 nt
	global_load_dwordx4 v[196:199], v[170:171], off nt
	global_load_dwordx4 v[200:203], v[170:171], off offset:528 nt
	global_load_dwordx4 v[204:207], v[170:171], off offset:512 nt
	v_cvt_pk_bf16_f32 v98, v102, v103
	v_cvt_pk_bf16_f32 v99, v104, v105
	v_cvt_pk_bf16_f32 v100, v106, v107
	v_cvt_pk_bf16_f32 v101, v108, v109
	v_lshl_add_u64 v[110:111], s[36:37], 0, v[120:121]
	global_store_dwordx4 v[110:111], v[98:101], off
	s_nop 1
	v_mul_f32_e32 v98, v103, v103
	v_mul_f32_e32 v99, v105, v105
	v_fmac_f32_e32 v98, v102, v102
	v_fmac_f32_e32 v99, v104, v104
	v_add_f32_e32 v98, v98, v99
	v_mul_f32_e32 v99, v107, v107
	v_fmac_f32_e32 v99, v106, v106
	v_add_f32_e32 v98, v99, v98
	v_mul_f32_e32 v99, v109, v109
	v_fmac_f32_e32 v99, v108, v108
	v_add_f32_e32 v98, v99, v98
	v_add_f32_e32 v98, v116, v98
	ds_bpermute_b32 v99, v158, v98
	s_waitcnt lgkmcnt(0)
	v_add_f32_e32 v98, v98, v99
	ds_bpermute_b32 v99, v157, v98
	s_and_saveexec_b64 s[26:27], s[0:1]
	s_cbranch_execz .LBB0_615
	s_waitcnt lgkmcnt(0)
	v_add_f32_e32 v98, v98, v99
	global_atomic_add_f32 v[114:115], v98, off offset:64
; __device__ __forceinline__ unsigned cvtpk(float lo, float hi) { f32x2_t v = {lo, hi}; bf16x2_t b = __builtin_convertvector(v, bf16x2_t); return __builtin_bit_cast(unsigned, b); }
; __device__ __forceinline__ float bflo(unsigned w) { return __uint_as_float(w << 16); }
; __device__ __forceinline__ float bfhi(unsigned w) { return __uint_as_float(w & 0xffff0000u); }
;     __device__ __forceinline__ void operator()(const f32x4 (&acc)[2][2][4][2], const Unit& u, int wr, int wc, int fr, int fq) const {
;     ...
;         for (int ai = 0; ai < 2; ++ai)
; #pragma unroll
;             for (int m = 0; m < 4; ++m) {
;                 const int row = row0 + ai * 128 + m * 16; float s = 0.f;
; #pragma unroll
;                 for (int bj = 0; bj < 2; ++bj) {
;                     const size_t off = (size_t)row * D + col0 + bj * 128;
;                     f32x4 b0, b1;
;                     if (BASE_F32) { b0 = __builtin_nontemporal_load((const f32x4*)(base + off)); b1 = __builtin_nontemporal_load((const f32x4*)(base + off + 4)); }
;                     else { const u32x4 w = *(const u32x4*)(xb + off); b0 = (f32x4){bflo(w.x), bfhi(w.x), bflo(w.y), bfhi(w.y)}; b1 = (f32x4){bflo(w.z), bfhi(w.z), bflo(w.w), bfhi(w.w)}; }
;                     const f32x4 h0 = b0 + acc[ai][bj][m][0] * scale, h1 = b1 + acc[ai][bj][m][1] * scale;
;                     if (OUT_F32) { *(f32x4*)(out + off) = h0; *(f32x4*)(out + off + 4) = h1; }
;                     else { u32x4 w; w.x = cvtpk(h0[0], h0[1]); w.y = cvtpk(h0[2], h0[3]); w.z = cvtpk(h1[0], h1[1]); w.w = cvtpk(h1[2], h1[3]); st16(xb + off, w); }
;                     s += (h0[0] * h0[0] + h0[1] * h0[1]) + (h0[2] * h0[2] + h0[3] * h0[3]) + (h1[0] * h1[0] + h1[1] * h1[1]) + (h1[2] * h1[2] + h1[3] * h1[3]);
;                 }
;                 s += __shfl_xor(s, 16); s += __shfl_xor(s, 32);
;                 if (fq == 0) __hip_atomic_fetch_add(ssq_out + row, s, __ATOMIC_RELAXED, __HIP_MEMORY_SCOPE_AGENT);
;             }
.LBB0_615:
	s_or_b64 exec, exec, s[26:27]
	v_or_b32_e32 v98, 32, v148
	s_waitcnt lgkmcnt(0)
	v_ashrrev_i32_e32 v99, 31, v98
	v_lshlrev_b64 v[106:107], 11, v[98:99]
	v_or_b32_e32 v106, v106, v159
	v_lshl_add_u64 v[108:109], v[106:107], 2, s[68:69]
	s_waitcnt vmcnt(15)
	v_pk_fma_f32 v[100:101], v[92:93], 0.5, v[210:211] op_sel_hi:[1,0,1]
	s_waitcnt vmcnt(14)
	v_pk_fma_f32 v[96:97], v[96:97], 0.5, v[214:215] op_sel_hi:[1,0,1]
	v_pk_fma_f32 v[94:95], v[94:95], 0.5, v[212:213] op_sel_hi:[1,0,1]
	v_pk_fma_f32 v[98:99], v[90:91], 0.5, v[208:209] op_sel_hi:[1,0,1]
	v_lshlrev_b64 v[102:103], 1, v[106:107]
	v_cvt_pk_bf16_f32 v90, v94, v95
	v_cvt_pk_bf16_f32 v91, v96, v97
	v_cvt_pk_bf16_f32 v92, v98, v99
	v_cvt_pk_bf16_f32 v93, v100, v101
	v_lshl_add_u64 v[104:105], s[36:37], 0, v[102:103]
	global_store_dwordx4 v[104:105], v[90:93], off
	v_or_b32_e32 v102, 0x100, v102
	s_nop 0
	v_mul_f32_e32 v90, v95, v95
	v_mul_f32_e32 v91, v97, v97
	v_fmac_f32_e32 v90, v94, v94
	v_fmac_f32_e32 v91, v96, v96
	v_add_f32_e32 v90, v90, v91
	v_mul_f32_e32 v91, v99, v99
	v_fmac_f32_e32 v91, v98, v98
	v_add_f32_e32 v90, v91, v90
	v_mul_f32_e32 v91, v101, v101
	v_fmac_f32_e32 v91, v100, v100
	v_add_f32_e32 v98, v91, v90
	s_waitcnt vmcnt(14)
	v_pk_fma_f32 v[92:93], v[84:85], 0.5, v[218:219] op_sel_hi:[1,0,1]
	s_waitcnt vmcnt(13)
	v_pk_fma_f32 v[88:89], v[88:89], 0.5, v[222:223] op_sel_hi:[1,0,1]
	v_pk_fma_f32 v[86:87], v[86:87], 0.5, v[220:221] op_sel_hi:[1,0,1]
	v_pk_fma_f32 v[90:91], v[82:83], 0.5, v[216:217] op_sel_hi:[1,0,1]
	s_mov_b64 s[100:101], 0x120000
	v_lshl_add_u64 v[170:171], v[168:169], 0, s[100:101]
	global_load_dwordx4 v[208:211], v[170:171], off offset:16 nt
	global_load_dwordx4 v[212:215], v[170:171], off nt
	global_load_dwordx4 v[216:219], v[170:171], off offset:528 nt
	global_load_dwordx4 v[220:223], v[170:171], off offset:512 nt
	v_cvt_pk_bf16_f32 v82, v86, v87
	v_cvt_pk_bf16_f32 v83, v88, v89
	v_cvt_pk_bf16_f32 v84, v90, v91
	v_cvt_pk_bf16_f32 v85, v92, v93
	v_lshl_add_u64 v[94:95], s[36:37], 0, v[102:103]
	global_store_dwordx4 v[94:95], v[82:85], off
	s_nop 1
	v_mul_f32_e32 v82, v87, v87
	v_mul_f32_e32 v83, v89, v89
	v_fmac_f32_e32 v82, v86, v86
	v_fmac_f32_e32 v83, v88, v88
	v_add_f32_e32 v82, v82, v83
	v_mul_f32_e32 v83, v91, v91
	v_fmac_f32_e32 v83, v90, v90
	v_add_f32_e32 v82, v83, v82
	v_mul_f32_e32 v83, v93, v93
	v_fmac_f32_e32 v83, v92, v92
	v_add_f32_e32 v82, v83, v82
	v_add_f32_e32 v82, v98, v82
	ds_bpermute_b32 v83, v158, v82
	s_waitcnt lgkmcnt(0)
	v_add_f32_e32 v82, v82, v83
	ds_bpermute_b32 v83, v157, v82
	s_and_saveexec_b64 s[26:27], s[0:1]
	s_cbranch_execz .LBB0_617
	s_waitcnt lgkmcnt(0)
	v_add_f32_e32 v82, v82, v83
	global_atomic_add_f32 v[114:115], v82, off offset:128
.LBB0_617:
	s_or_b64 exec, exec, s[26:27]
	v_or_b32_e32 v82, 48, v148
	s_waitcnt lgkmcnt(0)
	v_ashrrev_i32_e32 v83, 31, v82
	v_lshlrev_b64 v[90:91], 11, v[82:83]
	v_or_b32_e32 v90, v90, v159
	v_lshl_add_u64 v[92:93], v[90:91], 2, s[68:69]
	s_waitcnt vmcnt(16)
	v_pk_fma_f32 v[84:85], v[76:77], 0.5, v[174:175] op_sel_hi:[1,0,1]
	s_waitcnt vmcnt(15)
	v_pk_fma_f32 v[80:81], v[80:81], 0.5, v[178:179] op_sel_hi:[1,0,1]
	v_pk_fma_f32 v[78:79], v[78:79], 0.5, v[176:177] op_sel_hi:[1,0,1]
	v_pk_fma_f32 v[82:83], v[74:75], 0.5, v[172:173] op_sel_hi:[1,0,1]
	v_lshlrev_b64 v[86:87], 1, v[90:91]
	v_cvt_pk_bf16_f32 v74, v78, v79
	v_cvt_pk_bf16_f32 v75, v80, v81
	v_cvt_pk_bf16_f32 v76, v82, v83
	v_cvt_pk_bf16_f32 v77, v84, v85
	v_lshl_add_u64 v[88:89], s[36:37], 0, v[86:87]
	global_store_dwordx4 v[88:89], v[74:77], off
	v_or_b32_e32 v86, 0x100, v86
	s_nop 0
	v_mul_f32_e32 v74, v79, v79
	v_mul_f32_e32 v75, v81, v81
	v_fmac_f32_e32 v74, v78, v78
	v_fmac_f32_e32 v75, v80, v80
	v_add_f32_e32 v74, v74, v75
	v_mul_f32_e32 v75, v83, v83
	v_fmac_f32_e32 v75, v82, v82
	v_add_f32_e32 v74, v75, v74
	v_mul_f32_e32 v75, v85, v85
	v_fmac_f32_e32 v75, v84, v84
	v_add_f32_e32 v82, v75, v74
	s_waitcnt vmcnt(15)
	v_pk_fma_f32 v[76:77], v[68:69], 0.5, v[182:183] op_sel_hi:[1,0,1]
	s_waitcnt vmcnt(14)
	v_pk_fma_f32 v[72:73], v[72:73], 0.5, v[186:187] op_sel_hi:[1,0,1]
	v_pk_fma_f32 v[70:71], v[70:71], 0.5, v[184:185] op_sel_hi:[1,0,1]
	v_pk_fma_f32 v[74:75], v[66:67], 0.5, v[180:181] op_sel_hi:[1,0,1]
	s_mov_b64 s[100:101], 0x140000
	v_lshl_add_u64 v[170:171], v[168:169], 0, s[100:101]
	global_load_dwordx4 v[172:175], v[170:171], off offset:16 nt
	global_load_dwordx4 v[176:179], v[170:171], off nt
	global_load_dwordx4 v[180:183], v[170:171], off offset:528 nt
	global_load_dwordx4 v[184:187], v[170:171], off offset:512 nt
	v_cvt_pk_bf16_f32 v66, v70, v71
	v_cvt_pk_bf16_f32 v67, v72, v73
	v_cvt_pk_bf16_f32 v68, v74, v75
	v_cvt_pk_bf16_f32 v69, v76, v77
	v_lshl_add_u64 v[78:79], s[36:37], 0, v[86:87]
	global_store_dwordx4 v[78:79], v[66:69], off
	s_nop 1
	v_mul_f32_e32 v66, v71, v71
	v_mul_f32_e32 v67, v73, v73
	v_fmac_f32_e32 v66, v70, v70
	v_fmac_f32_e32 v67, v72, v72
	v_add_f32_e32 v66, v66, v67
	v_mul_f32_e32 v67, v75, v75
	v_fmac_f32_e32 v67, v74, v74
	v_add_f32_e32 v66, v67, v66
	v_mul_f32_e32 v67, v77, v77
	v_fmac_f32_e32 v67, v76, v76
	v_add_f32_e32 v66, v67, v66
	v_add_f32_e32 v66, v82, v66
	ds_bpermute_b32 v67, v158, v66
	s_waitcnt lgkmcnt(0)
	v_add_f32_e32 v66, v66, v67
	ds_bpermute_b32 v67, v157, v66
	s_and_saveexec_b64 s[26:27], s[0:1]
	s_cbranch_execz .LBB0_619
	s_waitcnt lgkmcnt(0)
	v_add_f32_e32 v66, v66, v67
	global_atomic_add_f32 v[114:115], v66, off offset:192
; __device__ __forceinline__ unsigned cvtpk(float lo, float hi) { f32x2_t v = {lo, hi}; bf16x2_t b = __builtin_convertvector(v, bf16x2_t); return __builtin_bit_cast(unsigned, b); }
; __device__ __forceinline__ float bflo(unsigned w) { return __uint_as_float(w << 16); }
; __device__ __forceinline__ float bfhi(unsigned w) { return __uint_as_float(w & 0xffff0000u); }
;     __device__ __forceinline__ void operator()(const f32x4 (&acc)[2][2][4][2], const Unit& u, int wr, int wc, int fr, int fq) const {
;     ...
;         for (int ai = 0; ai < 2; ++ai)
; #pragma unroll
;             for (int m = 0; m < 4; ++m) {
;                 const int row = row0 + ai * 128 + m * 16; float s = 0.f;
; #pragma unroll
;                 for (int bj = 0; bj < 2; ++bj) {
;                     const size_t off = (size_t)row * D + col0 + bj * 128;
;                     f32x4 b0, b1;
;                     if (BASE_F32) { b0 = __builtin_nontemporal_load((const f32x4*)(base + off)); b1 = __builtin_nontemporal_load((const f32x4*)(base + off + 4)); }
;                     else { const u32x4 w = *(const u32x4*)(xb + off); b0 = (f32x4){bflo(w.x), bfhi(w.x), bflo(w.y), bfhi(w.y)}; b1 = (f32x4){bflo(w.z), bfhi(w.z), bflo(w.w), bfhi(w.w)}; }
;                     const f32x4 h0 = b0 + acc[ai][bj][m][0] * scale, h1 = b1 + acc[ai][bj][m][1] * scale;
;                     if (OUT_F32) { *(f32x4*)(out + off) = h0; *(f32x4*)(out + off + 4) = h1; }
;                     else { u32x4 w; w.x = cvtpk(h0[0], h0[1]); w.y = cvtpk(h0[2], h0[3]); w.z = cvtpk(h1[0], h1[1]); w.w = cvtpk(h1[2], h1[3]); st16(xb + off, w); }
;                     s += (h0[0] * h0[0] + h0[1] * h0[1]) + (h0[2] * h0[2] + h0[3] * h0[3]) + (h1[0] * h1[0] + h1[1] * h1[1]) + (h1[2] * h1[2] + h1[3] * h1[3]);
;                 }
;                 s += __shfl_xor(s, 16); s += __shfl_xor(s, 32);
;                 if (fq == 0) __hip_atomic_fetch_add(ssq_out + row, s, __ATOMIC_RELAXED, __HIP_MEMORY_SCOPE_AGENT);
;             }
.LBB0_619:
	s_or_b64 exec, exec, s[26:27]
	s_mov_b64 s[26:27], 0x40000
	v_lshl_add_u64 v[74:75], v[146:147], 0, s[26:27]
	v_lshl_add_u64 v[76:77], v[74:75], 2, s[68:69]
	s_waitcnt lgkmcnt(0)
	s_waitcnt vmcnt(16)
	v_pk_fma_f32 v[68:69], v[60:61], 0.5, v[194:195] op_sel_hi:[1,0,1]
	s_waitcnt vmcnt(15)
	v_pk_fma_f32 v[64:65], v[64:65], 0.5, v[198:199] op_sel_hi:[1,0,1]
	v_pk_fma_f32 v[62:63], v[62:63], 0.5, v[196:197] op_sel_hi:[1,0,1]
	v_pk_fma_f32 v[66:67], v[58:59], 0.5, v[192:193] op_sel_hi:[1,0,1]
	v_lshlrev_b64 v[70:71], 1, v[74:75]
	v_cvt_pk_bf16_f32 v58, v62, v63
	v_cvt_pk_bf16_f32 v59, v64, v65
	v_cvt_pk_bf16_f32 v60, v66, v67
	v_cvt_pk_bf16_f32 v61, v68, v69
	v_lshl_add_u64 v[72:73], s[36:37], 0, v[70:71]
	global_store_dwordx4 v[72:73], v[58:61], off
	v_or_b32_e32 v70, 0x100, v70
	s_nop 0
	v_mul_f32_e32 v58, v63, v63
	v_mul_f32_e32 v59, v65, v65
	v_fmac_f32_e32 v58, v62, v62
	v_fmac_f32_e32 v59, v64, v64
	v_add_f32_e32 v58, v58, v59
	v_mul_f32_e32 v59, v67, v67
	v_fmac_f32_e32 v59, v66, v66
	v_add_f32_e32 v58, v59, v58
	v_mul_f32_e32 v59, v69, v69
	v_fmac_f32_e32 v59, v68, v68
	v_add_f32_e32 v66, v59, v58
	s_waitcnt vmcnt(15)
	v_pk_fma_f32 v[60:61], v[52:53], 0.5, v[202:203] op_sel_hi:[1,0,1]
	s_waitcnt vmcnt(14)
	v_pk_fma_f32 v[56:57], v[56:57], 0.5, v[206:207] op_sel_hi:[1,0,1]
	v_pk_fma_f32 v[54:55], v[54:55], 0.5, v[204:205] op_sel_hi:[1,0,1]
	v_pk_fma_f32 v[58:59], v[50:51], 0.5, v[200:201] op_sel_hi:[1,0,1]
	s_mov_b64 s[100:101], 0x160000
	v_lshl_add_u64 v[170:171], v[168:169], 0, s[100:101]
	global_load_dwordx4 v[192:195], v[170:171], off offset:16 nt
	global_load_dwordx4 v[196:199], v[170:171], off nt
	global_load_dwordx4 v[200:203], v[170:171], off offset:528 nt
	global_load_dwordx4 v[204:207], v[170:171], off offset:512 nt
	v_cvt_pk_bf16_f32 v50, v54, v55
	v_cvt_pk_bf16_f32 v51, v56, v57
	v_cvt_pk_bf16_f32 v52, v58, v59
	v_cvt_pk_bf16_f32 v53, v60, v61
	v_lshl_add_u64 v[62:63], s[36:37], 0, v[70:71]
	global_store_dwordx4 v[62:63], v[50:53], off
	s_nop 1
	v_mul_f32_e32 v50, v55, v55
	v_mul_f32_e32 v51, v57, v57
	v_fmac_f32_e32 v50, v54, v54
	v_fmac_f32_e32 v51, v56, v56
	v_add_f32_e32 v50, v50, v51
	v_mul_f32_e32 v51, v59, v59
	v_fmac_f32_e32 v51, v58, v58
	v_add_f32_e32 v50, v51, v50
	v_mul_f32_e32 v51, v61, v61
	v_fmac_f32_e32 v51, v60, v60
	v_add_f32_e32 v50, v51, v50
	v_add_f32_e32 v50, v66, v50
	ds_bpermute_b32 v51, v158, v50
	s_waitcnt lgkmcnt(0)
	v_add_f32_e32 v50, v50, v51
	ds_bpermute_b32 v51, v157, v50
	s_and_saveexec_b64 s[26:27], s[0:1]
	s_cbranch_execz .LBB0_621
	s_waitcnt lgkmcnt(0)
	v_add_f32_e32 v50, v50, v51
	global_atomic_add_f32 v[114:115], v50, off offset:512
.LBB0_621:
	s_or_b64 exec, exec, s[26:27]
	s_mov_b64 s[26:27], 0x48000
	v_lshl_add_u64 v[58:59], v[146:147], 0, s[26:27]
	v_lshl_add_u64 v[60:61], v[58:59], 2, s[68:69]
	s_waitcnt lgkmcnt(0)
	s_waitcnt vmcnt(16)
	v_pk_fma_f32 v[52:53], v[44:45], 0.5, v[210:211] op_sel_hi:[1,0,1]
	s_waitcnt vmcnt(15)
	v_pk_fma_f32 v[48:49], v[48:49], 0.5, v[214:215] op_sel_hi:[1,0,1]
	v_pk_fma_f32 v[46:47], v[46:47], 0.5, v[212:213] op_sel_hi:[1,0,1]
	v_pk_fma_f32 v[50:51], v[42:43], 0.5, v[208:209] op_sel_hi:[1,0,1]
	v_lshlrev_b64 v[54:55], 1, v[58:59]
	v_cvt_pk_bf16_f32 v42, v46, v47
	v_cvt_pk_bf16_f32 v43, v48, v49
	v_cvt_pk_bf16_f32 v44, v50, v51
	v_cvt_pk_bf16_f32 v45, v52, v53
	v_lshl_add_u64 v[56:57], s[36:37], 0, v[54:55]
	global_store_dwordx4 v[56:57], v[42:45], off
	v_or_b32_e32 v54, 0x100, v54
	s_nop 0
	v_mul_f32_e32 v42, v47, v47
	v_mul_f32_e32 v43, v49, v49
	v_fmac_f32_e32 v42, v46, v46
	v_fmac_f32_e32 v43, v48, v48
	v_add_f32_e32 v42, v42, v43
	v_mul_f32_e32 v43, v51, v51
	v_fmac_f32_e32 v43, v50, v50
	v_add_f32_e32 v42, v43, v42
	v_mul_f32_e32 v43, v53, v53
	v_fmac_f32_e32 v43, v52, v52
	v_add_f32_e32 v50, v43, v42
	s_waitcnt vmcnt(15)
	v_pk_fma_f32 v[44:45], v[36:37], 0.5, v[218:219] op_sel_hi:[1,0,1]
	s_waitcnt vmcnt(14)
	v_pk_fma_f32 v[40:41], v[40:41], 0.5, v[222:223] op_sel_hi:[1,0,1]
	v_pk_fma_f32 v[38:39], v[38:39], 0.5, v[220:221] op_sel_hi:[1,0,1]
	v_pk_fma_f32 v[42:43], v[34:35], 0.5, v[216:217] op_sel_hi:[1,0,1]
	v_cvt_pk_bf16_f32 v34, v38, v39
	v_cvt_pk_bf16_f32 v35, v40, v41
	v_cvt_pk_bf16_f32 v36, v42, v43
	v_cvt_pk_bf16_f32 v37, v44, v45
	v_lshl_add_u64 v[46:47], s[36:37], 0, v[54:55]
	global_store_dwordx4 v[46:47], v[34:37], off
	s_nop 1
	v_mul_f32_e32 v34, v39, v39
	v_mul_f32_e32 v35, v41, v41
	v_fmac_f32_e32 v34, v38, v38
	v_fmac_f32_e32 v35, v40, v40
	v_add_f32_e32 v34, v34, v35
	v_mul_f32_e32 v35, v43, v43
	v_fmac_f32_e32 v35, v42, v42
	v_add_f32_e32 v34, v35, v34
	v_mul_f32_e32 v35, v45, v45
	v_fmac_f32_e32 v35, v44, v44
	v_add_f32_e32 v34, v35, v34
	v_add_f32_e32 v34, v50, v34
	ds_bpermute_b32 v35, v158, v34
	s_waitcnt lgkmcnt(0)
	v_add_f32_e32 v34, v34, v35
	ds_bpermute_b32 v35, v157, v34
	s_and_saveexec_b64 s[26:27], s[0:1]
	s_cbranch_execz .LBB0_623
	s_waitcnt lgkmcnt(0)
	v_add_f32_e32 v34, v34, v35
	global_atomic_add_f32 v[114:115], v34, off offset:576
; __device__ __forceinline__ unsigned cvtpk(float lo, float hi) { f32x2_t v = {lo, hi}; bf16x2_t b = __builtin_convertvector(v, bf16x2_t); return __builtin_bit_cast(unsigned, b); }
; __device__ __forceinline__ float bflo(unsigned w) { return __uint_as_float(w << 16); }
; __device__ __forceinline__ float bfhi(unsigned w) { return __uint_as_float(w & 0xffff0000u); }
;     __device__ __forceinline__ void operator()(const f32x4 (&acc)[2][2][4][2], const Unit& u, int wr, int wc, int fr, int fq) const {
;     ...
;         for (int ai = 0; ai < 2; ++ai)
; #pragma unroll
;             for (int m = 0; m < 4; ++m) {
;                 const int row = row0 + ai * 128 + m * 16; float s = 0.f;
; #pragma unroll
;                 for (int bj = 0; bj < 2; ++bj) {
;                     const size_t off = (size_t)row * D + col0 + bj * 128;
;                     f32x4 b0, b1;
;                     if (BASE_F32) { b0 = __builtin_nontemporal_load((const f32x4*)(base + off)); b1 = __builtin_nontemporal_load((const f32x4*)(base + off + 4)); }
;                     else { const u32x4 w = *(const u32x4*)(xb + off); b0 = (f32x4){bflo(w.x), bfhi(w.x), bflo(w.y), bfhi(w.y)}; b1 = (f32x4){bflo(w.z), bfhi(w.z), bflo(w.w), bfhi(w.w)}; }
;                     const f32x4 h0 = b0 + acc[ai][bj][m][0] * scale, h1 = b1 + acc[ai][bj][m][1] * scale;
;                     if (OUT_F32) { *(f32x4*)(out + off) = h0; *(f32x4*)(out + off + 4) = h1; }
;                     else { u32x4 w; w.x = cvtpk(h0[0], h0[1]); w.y = cvtpk(h0[2], h0[3]); w.z = cvtpk(h1[0], h1[1]); w.w = cvtpk(h1[2], h1[3]); st16(xb + off, w); }
;                     s += (h0[0] * h0[0] + h0[1] * h0[1]) + (h0[2] * h0[2] + h0[3] * h0[3]) + (h1[0] * h1[0] + h1[1] * h1[1]) + (h1[2] * h1[2] + h1[3] * h1[3]);
;                 }
;                 s += __shfl_xor(s, 16); s += __shfl_xor(s, 32);
;                 if (fq == 0) __hip_atomic_fetch_add(ssq_out + row, s, __ATOMIC_RELAXED, __HIP_MEMORY_SCOPE_AGENT);
;             }
.LBB0_623:
	s_or_b64 exec, exec, s[26:27]
	s_mov_b64 s[26:27], 0x50000
	v_lshl_add_u64 v[42:43], v[146:147], 0, s[26:27]
	v_lshl_add_u64 v[44:45], v[42:43], 2, s[68:69]
	s_waitcnt lgkmcnt(0)
	s_waitcnt vmcnt(12)
	v_pk_fma_f32 v[36:37], v[28:29], 0.5, v[174:175] op_sel_hi:[1,0,1]
	s_waitcnt vmcnt(11)
	v_pk_fma_f32 v[32:33], v[32:33], 0.5, v[178:179] op_sel_hi:[1,0,1]
	v_pk_fma_f32 v[30:31], v[30:31], 0.5, v[176:177] op_sel_hi:[1,0,1]
	v_pk_fma_f32 v[34:35], v[26:27], 0.5, v[172:173] op_sel_hi:[1,0,1]
	v_lshlrev_b64 v[38:39], 1, v[42:43]
	v_cvt_pk_bf16_f32 v26, v30, v31
	v_cvt_pk_bf16_f32 v27, v32, v33
	v_cvt_pk_bf16_f32 v28, v34, v35
	v_cvt_pk_bf16_f32 v29, v36, v37
	v_lshl_add_u64 v[40:41], s[36:37], 0, v[38:39]
	global_store_dwordx4 v[40:41], v[26:29], off
	v_or_b32_e32 v38, 0x100, v38
	s_nop 0
	v_mul_f32_e32 v26, v31, v31
	v_mul_f32_e32 v27, v33, v33
	v_fmac_f32_e32 v26, v30, v30
	v_fmac_f32_e32 v27, v32, v32
	v_add_f32_e32 v26, v26, v27
	v_mul_f32_e32 v27, v35, v35
	v_fmac_f32_e32 v27, v34, v34
	v_add_f32_e32 v26, v27, v26
	v_mul_f32_e32 v27, v37, v37
	v_fmac_f32_e32 v27, v36, v36
	v_add_f32_e32 v34, v27, v26
	s_waitcnt vmcnt(11)
	v_pk_fma_f32 v[28:29], v[20:21], 0.5, v[182:183] op_sel_hi:[1,0,1]
	s_waitcnt vmcnt(10)
	v_pk_fma_f32 v[24:25], v[24:25], 0.5, v[186:187] op_sel_hi:[1,0,1]
	v_pk_fma_f32 v[22:23], v[22:23], 0.5, v[184:185] op_sel_hi:[1,0,1]
	v_pk_fma_f32 v[26:27], v[18:19], 0.5, v[180:181] op_sel_hi:[1,0,1]
	v_cvt_pk_bf16_f32 v18, v22, v23
	v_cvt_pk_bf16_f32 v19, v24, v25
	v_cvt_pk_bf16_f32 v20, v26, v27
	v_cvt_pk_bf16_f32 v21, v28, v29
	v_lshl_add_u64 v[30:31], s[36:37], 0, v[38:39]
	global_store_dwordx4 v[30:31], v[18:21], off
	s_nop 1
	v_mul_f32_e32 v18, v23, v23
	v_mul_f32_e32 v19, v25, v25
	v_fmac_f32_e32 v18, v22, v22
	v_fmac_f32_e32 v19, v24, v24
	v_add_f32_e32 v18, v18, v19
	v_mul_f32_e32 v19, v27, v27
	v_fmac_f32_e32 v19, v26, v26
	v_add_f32_e32 v18, v19, v18
	v_mul_f32_e32 v19, v29, v29
	v_fmac_f32_e32 v19, v28, v28
	v_add_f32_e32 v18, v19, v18
	v_add_f32_e32 v18, v34, v18
	ds_bpermute_b32 v19, v158, v18
	s_waitcnt lgkmcnt(0)
	v_add_f32_e32 v18, v18, v19
	ds_bpermute_b32 v19, v157, v18
	s_and_saveexec_b64 s[26:27], s[0:1]
	s_cbranch_execz .LBB0_625
	s_waitcnt lgkmcnt(0)
	v_add_f32_e32 v18, v18, v19
	global_atomic_add_f32 v[114:115], v18, off offset:640
.LBB0_625:
	s_or_b64 exec, exec, s[26:27]
	s_mov_b64 s[26:27], 0x58000
	v_lshl_add_u64 v[26:27], v[146:147], 0, s[26:27]
	v_lshl_add_u64 v[28:29], v[26:27], 2, s[68:69]
	s_waitcnt lgkmcnt(0)
	s_waitcnt vmcnt(8)
	v_pk_fma_f32 v[20:21], v[12:13], 0.5, v[194:195] op_sel_hi:[1,0,1]
	s_waitcnt vmcnt(7)
	v_pk_fma_f32 v[16:17], v[16:17], 0.5, v[198:199] op_sel_hi:[1,0,1]
	v_pk_fma_f32 v[14:15], v[14:15], 0.5, v[196:197] op_sel_hi:[1,0,1]
	v_pk_fma_f32 v[18:19], v[10:11], 0.5, v[192:193] op_sel_hi:[1,0,1]
	v_lshlrev_b64 v[22:23], 1, v[26:27]
	v_cvt_pk_bf16_f32 v10, v14, v15
	v_cvt_pk_bf16_f32 v11, v16, v17
	v_cvt_pk_bf16_f32 v12, v18, v19
	v_cvt_pk_bf16_f32 v13, v20, v21
	v_lshl_add_u64 v[24:25], s[36:37], 0, v[22:23]
	global_store_dwordx4 v[24:25], v[10:13], off
	v_or_b32_e32 v22, 0x100, v22
	s_nop 0
	v_mul_f32_e32 v10, v15, v15
	v_mul_f32_e32 v11, v17, v17
	v_fmac_f32_e32 v10, v14, v14
	v_fmac_f32_e32 v11, v16, v16
	v_add_f32_e32 v10, v10, v11
	v_mul_f32_e32 v11, v19, v19
	v_fmac_f32_e32 v11, v18, v18
	v_add_f32_e32 v10, v11, v10
	v_mul_f32_e32 v11, v21, v21
	v_fmac_f32_e32 v11, v20, v20
	v_add_f32_e32 v18, v11, v10
	s_waitcnt vmcnt(7)
	v_pk_fma_f32 v[12:13], v[4:5], 0.5, v[202:203] op_sel_hi:[1,0,1]
	s_waitcnt vmcnt(6)
	v_pk_fma_f32 v[8:9], v[8:9], 0.5, v[206:207] op_sel_hi:[1,0,1]
	v_pk_fma_f32 v[6:7], v[6:7], 0.5, v[204:205] op_sel_hi:[1,0,1]
	v_pk_fma_f32 v[10:11], v[2:3], 0.5, v[200:201] op_sel_hi:[1,0,1]
	v_cvt_pk_bf16_f32 v2, v6, v7
	v_cvt_pk_bf16_f32 v3, v8, v9
	v_cvt_pk_bf16_f32 v4, v10, v11
	v_cvt_pk_bf16_f32 v5, v12, v13
	v_lshl_add_u64 v[14:15], s[36:37], 0, v[22:23]
	global_store_dwordx4 v[14:15], v[2:5], off
	s_nop 1
	v_mul_f32_e32 v2, v7, v7
	v_mul_f32_e32 v3, v9, v9
	v_fmac_f32_e32 v2, v6, v6
	v_fmac_f32_e32 v3, v8, v8
	v_add_f32_e32 v2, v2, v3
	v_mul_f32_e32 v3, v11, v11
	v_fmac_f32_e32 v3, v10, v10
	v_add_f32_e32 v2, v3, v2
	v_mul_f32_e32 v3, v13, v13
	v_fmac_f32_e32 v3, v12, v12
	v_add_f32_e32 v2, v3, v2
	v_add_f32_e32 v2, v18, v2
	ds_bpermute_b32 v3, v158, v2
	s_waitcnt lgkmcnt(0)
	v_add_f32_e32 v2, v2, v3
	ds_bpermute_b32 v3, v157, v2
	s_and_saveexec_b64 s[26:27], s[0:1]
	s_cbranch_execz .LBB0_627
	s_waitcnt lgkmcnt(0)
	v_add_f32_e32 v2, v2, v3
	global_atomic_add_f32 v[114:115], v2, off offset:704
